# P3 K-loop: B-tile and As[0][1] LDS-DMA loads in SGPR-base (s pair or vcc) + VGPR-offset form
# baseline (speedup 1.0000x reference)
; #define PG8_STAGE(bufoff, gbase, voff) do { _Pragma("unroll") for (int _i = 0; _i < 2; ++_i) \
;         __builtin_amdgcn_global_load_lds((const unsigned*)((const char*)(gbase) + (voff)[_i]), (PG8_LAS unsigned*)(lds + (bufoff) + ldsw + _i * 8192), 16, 0, 0); } while (0)
; #define PG8_LDA(dst, b, h) do { _Pragma("unroll") for (int m = 0; m < 4; ++m) _Pragma("unroll") for (int k = 0; k < 2; ++k) dst[m][k] = *(const PG8_LAS bf16x8*)(lds + PG8_SA(b, h) + aoff + m * 2048 + k * 1024); } while (0)
; #define PG8_LDB(dst, b, h) do { _Pragma("unroll") for (int n = 0; n < 2; ++n) _Pragma("unroll") for (int k = 0; k < 2; ++k) dst[n][k] = *(const PG8_LAS bf16x8*)(lds + PG8_SB(b, h) + boff + n * 2048 + k * 1024); } while (0)
; #define PG8_MMA(ai, bj, At, Bt) do { __builtin_amdgcn_s_setprio(1); _Pragma("unroll") for (int m = 0; m < 4; ++m) _Pragma("unroll") for (int n = 0; n < 2; ++n) _Pragma("unroll") for (int k = 0; k < 2; ++k) \
;         acc[ai][bj][m][n] = __builtin_amdgcn_mfma_f32_16x16x32_bf16(Bt[n][k], At[m][k], acc[ai][bj][m][n], 0, 0, 0); __builtin_amdgcn_s_setprio(0); } while (0)
; #define PG8_WAIT_V(n) asm volatile("s_waitcnt vmcnt(" #n ")" ::: "memory")
; #define PG8_WAIT_L(n) asm volatile("s_waitcnt lgkmcnt(" #n ")" ::: "memory")
; #define PG8_BAR __builtin_amdgcn_s_barrier()
; template <class Epi, class Sched, bool ALIGN_EPI = false, bool SP2 = false>
; __device__ __forceinline__ void gemm_phase(PG8_LAS unsigned char* lds, const Gemm g, const Sched& S, const Epi& E) {
;     ...
;             const char* a1 = cA + (size_t)(t + 1) * kstep;
;             const char* a2 = last ? nA : cA + (size_t)(t + 2) * kstep; const char* b2 = last ? nB : cB + (size_t)(t + 2) * kstep;
;             const char* a3 = a2 + kstep; const char* b3 = b2 + kstep;
;             if (last && has_next) S.a_ready(nxt);
;             if constexpr (SP2) {
;             PG8_LDB(B0, 0, 0); PG8_LDB(B1, 0, 1); PG8_SCHED; PG8_LDA(At, 0, 0); PG8_STAGE(PG8_SA(1, 1), a1 + hstepA, voffA);
;             PG8_WAIT_V(8); PG8_WAIT_L(0); PG8_BAR; PG8_MMA(0, 0, At, B0); PG8_MMA(0, 1, At, B1); PG8_BAR; PG8_SCHED;
;             PG8_LDA(At, 0, 1); PG8_STAGE(PG8_SB(0, 0), b2, voffB); PG8_STAGE(PG8_SB(0, 1), b2 + hstepB, voffB); PG8_STAGE(PG8_SA(0, 0), a2, voffA);
;             PG8_WAIT_V(8); PG8_WAIT_L(0); PG8_BAR; PG8_MMA(1, 0, At, B0); PG8_MMA(1, 1, At, B1); PG8_BAR; PG8_SCHED;
.LBB0_1217:
	v_add_u32_e32 v1, s57, v154
	ds_read_b128 v[158:161], v1
	ds_read_b128 v[162:165], v1 offset:1024
	ds_read_b128 v[166:169], v1 offset:2048
	ds_read_b128 v[170:173], v1 offset:3072
	v_add_u32_e32 v1, s58, v154
	s_add_u32 s42, s78, s18
	ds_read_b128 v[174:177], v1
	ds_read_b128 v[178:181], v1 offset:1024
	ds_read_b128 v[182:185], v1 offset:2048
	ds_read_b128 v[186:189], v1 offset:3072
	s_addc_u32 s43, s79, s19
	s_add_u32 s42, s42, 0x100
	s_addc_u32 s43, s43, 0
	s_add_u32 s69, s66, s18
	s_addc_u32 s70, s67, s19
	s_cmpk_eq_i32 s18, 0xf00
	s_cselect_b32 s43, s62, s43
	s_cselect_b32 s42, s63, s42
	s_cselect_b32 vcc_hi, s51, s70
	s_cselect_b32 vcc_lo, s65, s69
	v_lshl_add_u64 v[2:3], v[148:149], 0, s[18:19]
	s_add_i32 m0, s5, 0xc000
	ds_read_b128 v[190:193], v156
	ds_read_b128 v[194:197], v156 offset:1024
	ds_read_b128 v[198:201], v156 offset:2048
	ds_read_b128 v[202:205], v156 offset:3072
	ds_read_b128 v[206:209], v156 offset:4096
	ds_read_b128 v[210:213], v156 offset:5120
	ds_read_b128 v[214:217], v156 offset:6144
	ds_read_b128 v[218:221], v156 offset:7168
	s_add_u32 s98, s78, s18
	s_addc_u32 s99, s79, s19
	s_add_u32 s98, s98, 0x80
	s_addc_u32 s99, s99, 0
	s_mov_b32 m0, s47
	s_nop 0
	global_load_lds_dwordx4 v132, s[98:99]
	s_mov_b32 m0, s56
	s_nop 0
	global_load_lds_dwordx4 v136, s[98:99]
	s_add_i32 m0, s5, 0xc000
	s_nop 0
	global_load_lds_dwordx4 v[2:3], off
	v_lshl_add_u64 v[2:3], v[150:151], 0, s[18:19]
	s_add_i32 m0, s5, 0xe000
	s_nop 0
	global_load_lds_dwordx4 v[2:3], off
	s_waitcnt vmcnt(8)
	s_waitcnt lgkmcnt(0)
	s_barrier
	s_setprio 1
	s_waitcnt lgkmcnt(0)
	v_mfma_f32_16x16x32_bf16 v[128:131], v[158:161], v[190:193], v[128:131]
	v_mfma_f32_16x16x32_bf16 v[124:127], v[166:169], v[190:193], v[124:127]
	v_mfma_f32_16x16x32_bf16 v[112:115], v[158:161], v[198:201], v[112:115]
	v_mfma_f32_16x16x32_bf16 v[108:111], v[166:169], v[198:201], v[108:111]
	v_mfma_f32_16x16x32_bf16 v[96:99], v[158:161], v[206:209], v[96:99]
	v_mfma_f32_16x16x32_bf16 v[92:95], v[166:169], v[206:209], v[92:95]
	v_mfma_f32_16x16x32_bf16 v[80:83], v[158:161], v[214:217], v[80:83]
	v_mfma_f32_16x16x32_bf16 v[76:79], v[166:169], v[214:217], v[76:79]
	v_mfma_f32_16x16x32_bf16 v[128:131], v[162:165], v[194:197], v[128:131]
	v_mfma_f32_16x16x32_bf16 v[124:127], v[170:173], v[194:197], v[124:127]
	v_mfma_f32_16x16x32_bf16 v[112:115], v[162:165], v[202:205], v[112:115]
	v_mfma_f32_16x16x32_bf16 v[108:111], v[170:173], v[202:205], v[108:111]
	v_mfma_f32_16x16x32_bf16 v[96:99], v[162:165], v[210:213], v[96:99]
	v_mfma_f32_16x16x32_bf16 v[92:95], v[170:173], v[210:213], v[92:95]
	v_mfma_f32_16x16x32_bf16 v[80:83], v[162:165], v[218:221], v[80:83]
	v_mfma_f32_16x16x32_bf16 v[76:79], v[170:173], v[218:221], v[76:79]
	s_setprio 0
	s_setprio 1
	v_mfma_f32_16x16x32_bf16 v[120:123], v[174:177], v[190:193], v[120:123]
	v_mfma_f32_16x16x32_bf16 v[116:119], v[182:185], v[190:193], v[116:119]
	v_mfma_f32_16x16x32_bf16 v[104:107], v[174:177], v[198:201], v[104:107]
	v_mfma_f32_16x16x32_bf16 v[100:103], v[182:185], v[198:201], v[100:103]
	v_mfma_f32_16x16x32_bf16 v[88:91], v[174:177], v[206:209], v[88:91]
	v_mfma_f32_16x16x32_bf16 v[84:87], v[182:185], v[206:209], v[84:87]
	v_mfma_f32_16x16x32_bf16 v[72:75], v[174:177], v[214:217], v[72:75]
	v_mfma_f32_16x16x32_bf16 v[68:71], v[182:185], v[214:217], v[68:71]
	v_mfma_f32_16x16x32_bf16 v[120:123], v[178:181], v[194:197], v[120:123]
	v_mfma_f32_16x16x32_bf16 v[116:119], v[186:189], v[194:197], v[116:119]
	v_mfma_f32_16x16x32_bf16 v[104:107], v[178:181], v[202:205], v[104:107]
	v_mfma_f32_16x16x32_bf16 v[100:103], v[186:189], v[202:205], v[100:103]
	v_mfma_f32_16x16x32_bf16 v[88:91], v[178:181], v[210:213], v[88:91]
	v_mfma_f32_16x16x32_bf16 v[84:87], v[186:189], v[210:213], v[84:87]
	v_mfma_f32_16x16x32_bf16 v[72:75], v[178:181], v[218:221], v[72:75]
	v_mfma_f32_16x16x32_bf16 v[68:71], v[186:189], v[218:221], v[68:71]
	s_setprio 0
	s_barrier
	s_add_i32 s69, s57, s4
	s_mov_b32 m0, s69
	ds_read_b128 v[190:193], v156 offset:16384
	ds_read_b128 v[194:197], v156 offset:17408
	ds_read_b128 v[198:201], v156 offset:18432
	ds_read_b128 v[202:205], v156 offset:19456
	ds_read_b128 v[206:209], v156 offset:20480
	ds_read_b128 v[210:213], v156 offset:21504
	ds_read_b128 v[214:217], v156 offset:22528
	ds_read_b128 v[218:221], v156 offset:23552
	global_load_lds_dwordx4 v134, vcc
	s_add_i32 m0, s69, 0x2000
	s_add_u32 s70, vcc_lo, 0x80000
	s_addc_u32 s71, vcc_hi, 0
	s_add_i32 s69, s58, s4
	global_load_lds_dwordx4 v138, vcc
	s_mov_b32 m0, s69
	s_nop 0
	global_load_lds_dwordx4 v134, s[70:71]
	s_add_i32 m0, s69, 0x2000
	s_nop 0
	global_load_lds_dwordx4 v138, s[70:71]
	s_waitcnt vmcnt(6)
	s_waitcnt lgkmcnt(0)
	s_barrier
; #define PG8_STAGE(bufoff, gbase, voff) do { _Pragma("unroll") for (int _i = 0; _i < 2; ++_i) \
;         __builtin_amdgcn_global_load_lds((const unsigned*)((const char*)(gbase) + (voff)[_i]), (PG8_LAS unsigned*)(lds + (bufoff) + ldsw + _i * 8192), 16, 0, 0); } while (0)
; #define PG8_LDA(dst, b, h) do { _Pragma("unroll") for (int m = 0; m < 4; ++m) _Pragma("unroll") for (int k = 0; k < 2; ++k) dst[m][k] = *(const PG8_LAS bf16x8*)(lds + PG8_SA(b, h) + aoff + m * 2048 + k * 1024); } while (0)
; #define PG8_LDB(dst, b, h) do { _Pragma("unroll") for (int n = 0; n < 2; ++n) _Pragma("unroll") for (int k = 0; k < 2; ++k) dst[n][k] = *(const PG8_LAS bf16x8*)(lds + PG8_SB(b, h) + boff + n * 2048 + k * 1024); } while (0)
; #define PG8_MMA(ai, bj, At, Bt) do { __builtin_amdgcn_s_setprio(1); _Pragma("unroll") for (int m = 0; m < 4; ++m) _Pragma("unroll") for (int n = 0; n < 2; ++n) _Pragma("unroll") for (int k = 0; k < 2; ++k) \
;         acc[ai][bj][m][n] = __builtin_amdgcn_mfma_f32_16x16x32_bf16(Bt[n][k], At[m][k], acc[ai][bj][m][n], 0, 0, 0); __builtin_amdgcn_s_setprio(0); } while (0)
; #define PG8_WAIT_V(n) asm volatile("s_waitcnt vmcnt(" #n ")" ::: "memory")
; #define PG8_WAIT_L(n) asm volatile("s_waitcnt lgkmcnt(" #n ")" ::: "memory")
; #define PG8_BAR __builtin_amdgcn_s_barrier()
; #define PG8_SCHED __builtin_amdgcn_sched_barrier(0)
; template <class Epi, class Sched, bool ALIGN_EPI = false, bool SP2 = false>
; __device__ __forceinline__ void gemm_phase(PG8_LAS unsigned char* lds, const Gemm g, const Sched& S, const Epi& E) {
;     ...
;             PG8_WAIT_V(8); PG8_WAIT_L(0); PG8_BAR; PG8_MMA(0, 0, At, B0); PG8_MMA(0, 1, At, B1); PG8_BAR; PG8_SCHED;
;             PG8_LDA(At, 0, 1); PG8_STAGE(PG8_SB(0, 0), b2, voffB); PG8_STAGE(PG8_SB(0, 1), b2 + hstepB, voffB); PG8_STAGE(PG8_SA(0, 0), a2, voffA);
;             PG8_WAIT_V(8); PG8_WAIT_L(0); PG8_BAR; PG8_MMA(1, 0, At, B0); PG8_MMA(1, 1, At, B1); PG8_BAR; PG8_SCHED;
;             PG8_LDB(B0, 1, 0); PG8_LDB(B1, 1, 1); PG8_SCHED; PG8_LDA(At, 1, 0); PG8_STAGE(PG8_SA(0, 1), a2 + hstepA, voffA);
;             PG8_WAIT_V(8); PG8_WAIT_L(0); PG8_BAR; PG8_MMA(0, 0, At, B0); PG8_MMA(0, 1, At, B1); PG8_BAR; PG8_SCHED;
;             PG8_LDA(At, 1, 1); PG8_STAGE(PG8_SB(1, 0), b3, voffB); PG8_STAGE(PG8_SB(1, 1), b3 + hstepB, voffB); PG8_STAGE(PG8_SA(1, 0), a3, voffA);
	s_setprio 1
	s_waitcnt lgkmcnt(0)
	v_mfma_f32_16x16x32_bf16 v[64:67], v[158:161], v[190:193], v[64:67]
	v_mfma_f32_16x16x32_bf16 v[60:63], v[166:169], v[190:193], v[60:63]
	v_mfma_f32_16x16x32_bf16 v[48:51], v[158:161], v[198:201], v[48:51]
	v_mfma_f32_16x16x32_bf16 v[44:47], v[166:169], v[198:201], v[44:47]
	v_mfma_f32_16x16x32_bf16 v[32:35], v[158:161], v[206:209], v[32:35]
	v_mfma_f32_16x16x32_bf16 v[28:31], v[166:169], v[206:209], v[28:31]
	v_mfma_f32_16x16x32_bf16 v[16:19], v[158:161], v[214:217], v[16:19]
	v_mfma_f32_16x16x32_bf16 v[12:15], v[166:169], v[214:217], v[12:15]
	v_mfma_f32_16x16x32_bf16 v[64:67], v[162:165], v[194:197], v[64:67]
	v_mfma_f32_16x16x32_bf16 v[60:63], v[170:173], v[194:197], v[60:63]
	v_mfma_f32_16x16x32_bf16 v[48:51], v[162:165], v[202:205], v[48:51]
	v_mfma_f32_16x16x32_bf16 v[44:47], v[170:173], v[202:205], v[44:47]
	v_mfma_f32_16x16x32_bf16 v[32:35], v[162:165], v[210:213], v[32:35]
	v_mfma_f32_16x16x32_bf16 v[28:31], v[170:173], v[210:213], v[28:31]
	v_mfma_f32_16x16x32_bf16 v[16:19], v[162:165], v[218:221], v[16:19]
	v_mfma_f32_16x16x32_bf16 v[12:15], v[170:173], v[218:221], v[12:15]
	s_setprio 0
	s_setprio 1
	v_mfma_f32_16x16x32_bf16 v[56:59], v[174:177], v[190:193], v[56:59]
	v_mfma_f32_16x16x32_bf16 v[52:55], v[182:185], v[190:193], v[52:55]
	v_mfma_f32_16x16x32_bf16 v[40:43], v[174:177], v[198:201], v[40:43]
	v_mfma_f32_16x16x32_bf16 v[36:39], v[182:185], v[198:201], v[36:39]
	v_mfma_f32_16x16x32_bf16 v[24:27], v[174:177], v[206:209], v[24:27]
	v_mfma_f32_16x16x32_bf16 v[20:23], v[182:185], v[206:209], v[20:23]
	v_mfma_f32_16x16x32_bf16 v[8:11], v[174:177], v[214:217], v[8:11]
	v_mfma_f32_16x16x32_bf16 v[2:5], v[182:185], v[214:217], v[4:7]
	v_mfma_f32_16x16x32_bf16 v[56:59], v[178:181], v[194:197], v[56:59]
	v_mfma_f32_16x16x32_bf16 v[52:55], v[186:189], v[194:197], v[52:55]
	v_mfma_f32_16x16x32_bf16 v[40:43], v[178:181], v[202:205], v[40:43]
	v_mfma_f32_16x16x32_bf16 v[36:39], v[186:189], v[202:205], v[36:39]
	v_mfma_f32_16x16x32_bf16 v[24:27], v[178:181], v[210:213], v[24:27]
	v_mfma_f32_16x16x32_bf16 v[20:23], v[186:189], v[210:213], v[20:23]
	v_mfma_f32_16x16x32_bf16 v[8:11], v[178:181], v[218:221], v[8:11]
	v_mfma_f32_16x16x32_bf16 v[2:5], v[186:189], v[218:221], v[2:5]
	s_setprio 0
	s_barrier
	s_add_i32 s69, 0, 0x18000
	v_add_u32_e32 v1, s69, v154
	s_add_i32 s70, 0, 0x1c000
	ds_read_b128 v[158:161], v1
	ds_read_b128 v[162:165], v1 offset:1024
	ds_read_b128 v[166:169], v1 offset:2048
	ds_read_b128 v[170:173], v1 offset:3072
	v_add_u32_e32 v1, s70, v154
	ds_read_b128 v[174:177], v1
	ds_read_b128 v[178:181], v1 offset:1024
	ds_read_b128 v[182:185], v1 offset:2048
	ds_read_b128 v[186:189], v1 offset:3072
	s_mov_b64 s[100:101], s[42:43]
	s_add_u32 s42, s42, 0x80000
	s_addc_u32 s43, s43, 0
	s_mov_b32 m0, s7
	ds_read_b128 v[190:193], v156 offset:32768
	ds_read_b128 v[194:197], v156 offset:33792
	ds_read_b128 v[198:201], v156 offset:34816
	ds_read_b128 v[202:205], v156 offset:35840
	ds_read_b128 v[206:209], v156 offset:36864
	ds_read_b128 v[210:213], v156 offset:37888
	ds_read_b128 v[214:217], v156 offset:38912
	ds_read_b128 v[218:221], v156 offset:39936
	s_mov_b32 m0, s5
	s_nop 0
	global_load_lds_dwordx4 v132, s[100:101]
	s_mov_b32 m0, s6
	s_nop 0
	global_load_lds_dwordx4 v136, s[100:101]
	s_mov_b32 m0, s7
	s_nop 0
	global_load_lds_dwordx4 v132, s[42:43]
	s_mov_b32 m0, s33
	s_nop 0
	global_load_lds_dwordx4 v136, s[42:43]
	s_waitcnt vmcnt(8)
	s_waitcnt lgkmcnt(0)
	s_barrier
; #define PG8_STAGE(bufoff, gbase, voff) do { _Pragma("unroll") for (int _i = 0; _i < 2; ++_i) \
;         __builtin_amdgcn_global_load_lds((const unsigned*)((const char*)(gbase) + (voff)[_i]), (PG8_LAS unsigned*)(lds + (bufoff) + ldsw + _i * 8192), 16, 0, 0); } while (0)
; #define PG8_LDA(dst, b, h) do { _Pragma("unroll") for (int m = 0; m < 4; ++m) _Pragma("unroll") for (int k = 0; k < 2; ++k) dst[m][k] = *(const PG8_LAS bf16x8*)(lds + PG8_SA(b, h) + aoff + m * 2048 + k * 1024); } while (0)
; #define PG8_MMA(ai, bj, At, Bt) do { __builtin_amdgcn_s_setprio(1); _Pragma("unroll") for (int m = 0; m < 4; ++m) _Pragma("unroll") for (int n = 0; n < 2; ++n) _Pragma("unroll") for (int k = 0; k < 2; ++k) \
;         acc[ai][bj][m][n] = __builtin_amdgcn_mfma_f32_16x16x32_bf16(Bt[n][k], At[m][k], acc[ai][bj][m][n], 0, 0, 0); __builtin_amdgcn_s_setprio(0); } while (0)
; #define PG8_WAIT_V(n) asm volatile("s_waitcnt vmcnt(" #n ")" ::: "memory")
; #define PG8_WAIT_L(n) asm volatile("s_waitcnt lgkmcnt(" #n ")" ::: "memory")
; #define PG8_BAR __builtin_amdgcn_s_barrier()
; #define PG8_SCHED __builtin_amdgcn_sched_barrier(0)
; template <class Epi, class Sched, bool ALIGN_EPI = false, bool SP2 = false>
; __device__ __forceinline__ void gemm_phase(PG8_LAS unsigned char* lds, const Gemm g, const Sched& S, const Epi& E) {
;     ...
;         for (int t = 0; t < nt; t += 2) {
;     ...
;             PG8_WAIT_V(8); PG8_WAIT_L(0); PG8_BAR; PG8_MMA(0, 0, At, B0); PG8_MMA(0, 1, At, B1); PG8_BAR; PG8_SCHED;
;             PG8_LDA(At, 1, 1); PG8_STAGE(PG8_SB(1, 0), b3, voffB); PG8_STAGE(PG8_SB(1, 1), b3 + hstepB, voffB); PG8_STAGE(PG8_SA(1, 0), a3, voffA);
;             PG8_WAIT_V(8); PG8_WAIT_L(0); PG8_BAR; PG8_MMA(1, 0, At, B0); PG8_MMA(1, 1, At, B1); PG8_BAR; PG8_SCHED;
	s_setprio 1
	s_waitcnt lgkmcnt(0)
	v_mfma_f32_16x16x32_bf16 v[128:131], v[158:161], v[190:193], v[128:131]
	v_mfma_f32_16x16x32_bf16 v[124:127], v[166:169], v[190:193], v[124:127]
	v_mfma_f32_16x16x32_bf16 v[112:115], v[158:161], v[198:201], v[112:115]
	v_mfma_f32_16x16x32_bf16 v[108:111], v[166:169], v[198:201], v[108:111]
	v_mfma_f32_16x16x32_bf16 v[96:99], v[158:161], v[206:209], v[96:99]
	v_mfma_f32_16x16x32_bf16 v[92:95], v[166:169], v[206:209], v[92:95]
	v_mfma_f32_16x16x32_bf16 v[80:83], v[158:161], v[214:217], v[80:83]
	v_mfma_f32_16x16x32_bf16 v[76:79], v[166:169], v[214:217], v[76:79]
	v_mfma_f32_16x16x32_bf16 v[128:131], v[162:165], v[194:197], v[128:131]
	v_mfma_f32_16x16x32_bf16 v[124:127], v[170:173], v[194:197], v[124:127]
	v_mfma_f32_16x16x32_bf16 v[112:115], v[162:165], v[202:205], v[112:115]
	v_mfma_f32_16x16x32_bf16 v[108:111], v[170:173], v[202:205], v[108:111]
	v_mfma_f32_16x16x32_bf16 v[96:99], v[162:165], v[210:213], v[96:99]
	v_mfma_f32_16x16x32_bf16 v[92:95], v[170:173], v[210:213], v[92:95]
	v_mfma_f32_16x16x32_bf16 v[80:83], v[162:165], v[218:221], v[80:83]
	v_mfma_f32_16x16x32_bf16 v[76:79], v[170:173], v[218:221], v[76:79]
	s_setprio 0
	s_setprio 1
	v_mfma_f32_16x16x32_bf16 v[120:123], v[174:177], v[190:193], v[120:123]
	v_mfma_f32_16x16x32_bf16 v[116:119], v[182:185], v[190:193], v[116:119]
	v_mfma_f32_16x16x32_bf16 v[104:107], v[174:177], v[198:201], v[104:107]
	v_mfma_f32_16x16x32_bf16 v[100:103], v[182:185], v[198:201], v[100:103]
	v_mfma_f32_16x16x32_bf16 v[88:91], v[174:177], v[206:209], v[88:91]
	v_mfma_f32_16x16x32_bf16 v[84:87], v[182:185], v[206:209], v[84:87]
	v_mfma_f32_16x16x32_bf16 v[72:75], v[174:177], v[214:217], v[72:75]
	v_mfma_f32_16x16x32_bf16 v[68:71], v[182:185], v[214:217], v[68:71]
	v_mfma_f32_16x16x32_bf16 v[120:123], v[178:181], v[194:197], v[120:123]
	v_mfma_f32_16x16x32_bf16 v[116:119], v[186:189], v[194:197], v[116:119]
	v_mfma_f32_16x16x32_bf16 v[104:107], v[178:181], v[202:205], v[104:107]
	v_mfma_f32_16x16x32_bf16 v[100:103], v[186:189], v[202:205], v[100:103]
	v_mfma_f32_16x16x32_bf16 v[88:91], v[178:181], v[210:213], v[88:91]
	v_mfma_f32_16x16x32_bf16 v[84:87], v[186:189], v[210:213], v[84:87]
	v_mfma_f32_16x16x32_bf16 v[72:75], v[178:181], v[218:221], v[72:75]
	v_mfma_f32_16x16x32_bf16 v[68:71], v[186:189], v[218:221], v[68:71]
	s_setprio 0
	s_barrier
	s_add_i32 s42, s69, s4
	s_add_u32 s98, vcc_lo, 0x80
	s_addc_u32 s99, vcc_hi, 0
	s_mov_b32 m0, s42
	ds_read_b128 v[190:193], v156 offset:49152
	ds_read_b128 v[194:197], v156 offset:50176
	ds_read_b128 v[198:201], v156 offset:51200
	ds_read_b128 v[202:205], v156 offset:52224
	ds_read_b128 v[206:209], v156 offset:53248
	ds_read_b128 v[210:213], v156 offset:54272
	ds_read_b128 v[214:217], v156 offset:55296
	ds_read_b128 v[218:221], v156 offset:56320
	global_load_lds_dwordx4 v134, s[98:99]
	s_add_i32 m0, s42, 0x2000
	s_add_u32 s42, vcc_lo, 0x80080
	s_addc_u32 s43, vcc_hi, 0
	s_add_i32 s69, s70, s4
	global_load_lds_dwordx4 v138, s[98:99]
	s_mov_b32 m0, s69
	s_nop 0
	global_load_lds_dwordx4 v134, s[42:43]
	s_add_i32 m0, s69, 0x2000
	s_nop 0
	global_load_lds_dwordx4 v138, s[42:43]
	s_waitcnt vmcnt(6)
	s_waitcnt lgkmcnt(0)
	s_barrier
	s_setprio 1
	s_waitcnt lgkmcnt(0)
	v_mfma_f32_16x16x32_bf16 v[64:67], v[158:161], v[190:193], v[64:67]
	v_mfma_f32_16x16x32_bf16 v[60:63], v[166:169], v[190:193], v[60:63]
	v_mfma_f32_16x16x32_bf16 v[48:51], v[158:161], v[198:201], v[48:51]
	v_mfma_f32_16x16x32_bf16 v[44:47], v[166:169], v[198:201], v[44:47]
	v_mfma_f32_16x16x32_bf16 v[32:35], v[158:161], v[206:209], v[32:35]
	v_mfma_f32_16x16x32_bf16 v[28:31], v[166:169], v[206:209], v[28:31]
	v_mfma_f32_16x16x32_bf16 v[16:19], v[158:161], v[214:217], v[16:19]
	v_mfma_f32_16x16x32_bf16 v[12:15], v[166:169], v[214:217], v[12:15]
	v_mfma_f32_16x16x32_bf16 v[64:67], v[162:165], v[194:197], v[64:67]
	v_mfma_f32_16x16x32_bf16 v[60:63], v[170:173], v[194:197], v[60:63]
	v_mfma_f32_16x16x32_bf16 v[48:51], v[162:165], v[202:205], v[48:51]
	v_mfma_f32_16x16x32_bf16 v[44:47], v[170:173], v[202:205], v[44:47]
	v_mfma_f32_16x16x32_bf16 v[32:35], v[162:165], v[210:213], v[32:35]
	v_mfma_f32_16x16x32_bf16 v[28:31], v[170:173], v[210:213], v[28:31]
	v_mfma_f32_16x16x32_bf16 v[16:19], v[162:165], v[218:221], v[16:19]
	v_mfma_f32_16x16x32_bf16 v[12:15], v[170:173], v[218:221], v[12:15]
	s_setprio 0
	s_setprio 1
	v_mfma_f32_16x16x32_bf16 v[56:59], v[174:177], v[190:193], v[56:59]
	v_mfma_f32_16x16x32_bf16 v[52:55], v[182:185], v[190:193], v[52:55]
	v_mfma_f32_16x16x32_bf16 v[40:43], v[174:177], v[198:201], v[40:43]
	v_mfma_f32_16x16x32_bf16 v[36:39], v[182:185], v[198:201], v[36:39]
	v_mfma_f32_16x16x32_bf16 v[24:27], v[174:177], v[206:209], v[24:27]
	v_mfma_f32_16x16x32_bf16 v[20:23], v[182:185], v[206:209], v[20:23]
	v_mfma_f32_16x16x32_bf16 v[6:9], v[174:177], v[214:217], v[8:11]
	v_mfma_f32_16x16x32_bf16 v[2:5], v[182:185], v[214:217], v[2:5]
	v_mfma_f32_16x16x32_bf16 v[56:59], v[178:181], v[194:197], v[56:59]
	v_mfma_f32_16x16x32_bf16 v[52:55], v[186:189], v[194:197], v[52:55]
	v_mfma_f32_16x16x32_bf16 v[40:43], v[178:181], v[202:205], v[40:43]
	v_mfma_f32_16x16x32_bf16 v[36:39], v[186:189], v[202:205], v[36:39]
	v_mfma_f32_16x16x32_bf16 v[24:27], v[178:181], v[210:213], v[24:27]
	v_mfma_f32_16x16x32_bf16 v[20:23], v[186:189], v[210:213], v[20:23]
	v_mfma_f32_16x16x32_bf16 v[8:11], v[178:181], v[218:221], v[6:9]
	v_mfma_f32_16x16x32_bf16 v[4:7], v[186:189], v[218:221], v[2:5]
	s_setprio 0
	s_barrier
	s_add_i32 s68, s68, 2
	s_add_u32 s18, s18, 0x100
	s_addc_u32 s19, s19, 0
	s_cmp_gt_u32 s68, 29
	s_cbranch_scc1 .LBB0_1220
